# prologue: residual-stream copy fetches the four pieces of a row together
# speedup vs baseline: 1.0506x; 1.0038x over previous
; DI void prologue(PARAMS P, LAS unsigned char* lds, int wave, int lane) {
;     ...
;     for (int row = gw; row < MTOT; row += NGW) {
;         int g = 0, lr = row; if (row >= G0ROWS) { g = 1 + (row - G0ROWS) / GROWS; lr = (row - G0ROWS) % GROWS; }
;         const float* src = nullptr;
;         if (g != 0 || lr < 8192) src = P.in[0] + ((size_t)(4 * g + (lr >> 11)) * 2048 + (lr & 2047)) * D;
;         else if (lr < 8704) src = P.in[1] + (size_t)(lr - 8192) * D;
;         else if (lr < 8720) src = P.in[8] + (size_t)(lr - 8704) * D;
;         f32x4* dst = (f32x4*)(X + (size_t)row * D);
; #pragma unroll
;         for (int j = 0; j < 4; ++j) dst[lane + 64 * j] = src ? ((const f32x4*)src)[lane + 64 * j] : (f32x4){0.f, 0.f, 0.f, 0.f};
;     }
.LBB0_73:
	global_load_dwordx4 v[6:9], v1, s[22:23]
	global_load_dwordx4 v[12:15], v1, s[22:23] offset:1024
	global_load_dwordx4 v[16:19], v1, s[22:23] offset:2048
	global_load_dwordx4 v[20:23], v1, s[22:23] offset:3072
	s_waitcnt vmcnt(3)
	global_store_dwordx4 v[10:11], v[6:9], off offset:-2048
	s_waitcnt vmcnt(3)
	global_store_dwordx4 v[10:11], v[12:15], off offset:-1024
	s_waitcnt vmcnt(3)
	global_store_dwordx4 v[10:11], v[16:19], off
	s_waitcnt vmcnt(3)
	global_store_dwordx4 v[10:11], v[20:23], off offset:1024
	s_add_i32 s2, s2, s10
	s_cmp_lt_i32 s2, 0x8300
	v_lshl_add_u64 v[10:11], v[10:11], 0, s[16:17]
	s_cbranch_scc0 .LBB0_86
	s_branch .LBB0_70
